# b13 + counted vmcnt at epilogue constant-commit in INCV/UP0/UP1/KVQG (tile stores stay in flight)
# speedup vs baseline: 1.0186x; 1.0112x over previous
.LBB0_208:
	v_mov_b32_e32 v52, v100
	v_mov_b32_e32 v53, v100
	v_mov_b32_e32 v54, v101
	v_mov_b32_e32 v55, v101
	v_pk_mul_f32 v[12:13], v[12:13], v[52:53]
	v_pk_mul_f32 v[4:5], v[4:5], v[52:53]
	v_pk_mul_f32 v[8:9], v[8:9], v[54:55]
	v_pk_mul_f32 v[0:1], v[0:1], v[54:55]
	v_mov_b32_dpp v76, v80 row_shr:1 row_mask:0xf bank_mask:0xf
	v_mov_b32_dpp v77, v60 row_shr:1 row_mask:0xf bank_mask:0xf
	v_mov_b32_e32 v64, v100
	v_mov_b32_e32 v65, v100
	v_pk_mul_f32 v[4:5], v[12:13], v[4:5]
	v_mov_b32_e32 v100, v101
	v_pk_mul_f32 v[0:1], v[8:9], v[0:1]
	v_pk_mul_f32 v[8:9], v[20:21], v[76:77]
	v_pk_mul_f32 v[10:11], v[10:11], v[100:101]
	v_pk_mul_f32 v[2:3], v[2:3], v[100:101]
	v_fma_f32 v9, v4, v40, v9
	v_pk_mul_f32 v[2:3], v[10:11], v[2:3]
	v_add_f32_e32 v10, v8, v9
	v_mov_b32_e32 v8, v4
	v_mov_b32_e32 v9, v44
	v_mov_b32_e32 v76, v56
	v_pk_mul_f32 v[8:9], v[8:9], v[76:77]
	v_mov_b32_dpp v16, v81 row_shr:1 row_mask:0xf bank_mask:0xf
	v_fma_f32 v8, v0, v40, v8
	v_add_f32_e32 v11, v8, v9
	v_mov_b32_e32 v8, v4
	v_mov_b32_e32 v9, v0
	v_pk_mul_f32 v[8:9], v[8:9], v[20:21]
	v_mov_b32_dpp v17, v61 row_shr:1 row_mask:0xf bank_mask:0xf
	v_fma_f32 v4, v80, v40, v9
	v_add_f32_e32 v12, v8, v4
	v_mov_b32_e32 v8, v0
	v_mov_b32_e32 v9, v80
	v_pk_mul_f32 v[8:9], v[8:9], v[20:21]
	v_pk_mul_f32 v[14:15], v[14:15], v[64:65]
	v_fma_f32 v0, v60, v40, v9
	v_add_f32_e32 v13, v8, v0
	v_pk_mul_f32 v[8:9], v[22:23], v[16:17]
	v_pk_mul_f32 v[6:7], v[6:7], v[64:65]
	v_fma_f32 v0, v5, v41, v9
	v_mov_b32_e32 v44, v5
	v_mov_b32_e32 v16, v57
	v_pk_mul_f32 v[6:7], v[14:15], v[6:7]
	v_add_f32_e32 v14, v8, v0
	v_pk_mul_f32 v[8:9], v[44:45], v[16:17]
	v_mov_b32_e32 v80, v1
	v_fma_f32 v0, v1, v41, v8
	v_add_f32_e32 v8, v0, v9
	v_mov_b32_e32 v0, v5
	v_pk_mul_f32 v[4:5], v[0:1], v[22:23]
	v_mov_b32_dpp v30, v82 row_shr:1 row_mask:0xf bank_mask:0xf
	v_fma_f32 v0, v81, v41, v5
	v_add_f32_e32 v4, v4, v0
	v_pk_mul_f32 v[0:1], v[80:81], v[22:23]
	v_mov_b32_dpp v31, v62 row_shr:1 row_mask:0xf bank_mask:0xf
	v_fma_f32 v1, v61, v41, v1
	v_add_f32_e32 v5, v0, v1
	v_pk_mul_f32 v[0:1], v[24:25], v[30:31]
	v_mov_b32_e32 v30, v58
	v_fma_f32 v1, v6, v42, v1
	v_add_f32_e32 v9, v0, v1
	v_mov_b32_e32 v0, v6
	v_mov_b32_e32 v1, v46
	v_pk_mul_f32 v[0:1], v[0:1], v[30:31]
	v_mov_b32_dpp v18, v83 row_shr:1 row_mask:0xf bank_mask:0xf
	v_fma_f32 v0, v2, v42, v0
	v_add_f32_e32 v15, v0, v1
	v_mov_b32_e32 v0, v6
	v_mov_b32_e32 v1, v2
	v_pk_mul_f32 v[0:1], v[0:1], v[24:25]
	v_mov_b32_dpp v19, v63 row_shr:1 row_mask:0xf bank_mask:0xf
	v_fma_f32 v1, v82, v42, v1
	v_add_f32_e32 v6, v0, v1
	v_mov_b32_e32 v0, v2
	v_mov_b32_e32 v1, v82
	v_pk_mul_f32 v[0:1], v[0:1], v[24:25]
	v_mov_b32_e32 v46, v7
	v_fma_f32 v1, v62, v42, v1
	v_add_f32_e32 v16, v0, v1
	v_pk_mul_f32 v[0:1], v[26:27], v[18:19]
	v_mov_b32_e32 v18, v59
	v_fma_f32 v1, v7, v43, v1
	v_add_f32_e32 v17, v0, v1
	v_pk_mul_f32 v[0:1], v[46:47], v[18:19]
	v_mov_b32_e32 v2, v7
	v_fma_f32 v0, v3, v43, v0
	v_add_f32_e32 v18, v0, v1
	v_pk_mul_f32 v[0:1], v[2:3], v[26:27]
	v_mov_b32_e32 v82, v3
	v_fma_f32 v1, v83, v43, v1
	v_add_f32_e32 v7, v0, v1
	v_pk_mul_f32 v[0:1], v[82:83], v[26:27]
	v_cvt_pk_bf16_f32 v40, v10, v14
	v_cvt_pk_bf16_f32 v41, v9, v17
	s_nop 0
	v_fma_f32 v1, v63, v43, v1
	v_add_f32_e32 v19, v0, v1
	v_lshl_add_u64 v[0:1], v[74:75], 1, v[28:29]
	v_add_co_u32_e32 v2, vcc, s56, v0
	s_nop 1
	v_addc_co_u32_e32 v3, vcc, 0, v1, vcc
	v_add_co_u32_e32 v0, vcc, 0x41000, v0
	global_store_dwordx4 v[2:3], v[38:41], off nt
	s_nop 0
	v_addc_co_u32_e32 v1, vcc, 0, v1, vcc
	v_cvt_pk_bf16_f32 v38, v11, v8
	v_cvt_pk_bf16_f32 v39, v15, v18
	global_store_dwordx4 v[2:3], v[36:39], off offset:2048 nt
	s_nop 1
	v_cvt_pk_bf16_f32 v36, v12, v4
	v_cvt_pk_bf16_f32 v37, v6, v7
	global_store_dwordx4 v[0:1], v[34:37], off nt
	s_nop 1
	v_cvt_pk_bf16_f32 v34, v13, v5
	v_cvt_pk_bf16_f32 v35, v16, v19
	global_store_dwordx4 v[0:1], v[32:35], off offset:2048 nt
	s_and_b64 vcc, exec, s[8:9]
	s_mov_b64 s[8:9], -1
	s_cbranch_vccnz .LBB0_189
	s_xor_b32 s8, s15, 0x1000
	s_add_i32 s15, s8, 0
	s_add_i32 s15, s15, 0x24010
	s_and_saveexec_b64 s[8:9], s[2:3]
	s_cbranch_execz .LBB0_211
	v_add3_u32 v0, s15, v161, v146
	s_waitcnt vmcnt(8)
	ds_write_b128 v0, v[48:51]
.LBB0_211:
	s_or_b64 exec, exec, s[8:9]
	s_and_saveexec_b64 s[8:9], s[4:5]
	s_xor_b64 s[8:9], exec, s[8:9]
	s_cbranch_execz .LBB0_188
	v_lshl_add_u32 v0, v154, 2, s15
	s_waitcnt vmcnt(8)
	ds_write_b32 v0, v162 offset:3072
	s_branch .LBB0_188

.LBB0_469:
	v_mov_b32_e32 v88, v68
	v_mov_b32_e32 v89, v68
	v_mov_b32_e32 v92, v68
	v_mov_b32_e32 v93, v68
	v_pk_mul_f32 v[12:13], v[12:13], v[88:89]
	v_pk_mul_f32 v[88:89], v[4:5], v[88:89]
	v_mov_b32_e32 v68, v69
	v_mov_b32_dpp v79, v52 row_shr:1 row_mask:0xf bank_mask:0xf
	v_mov_b32_dpp v78, v56 row_shr:1 row_mask:0xf bank_mask:0xf
	v_mov_b32_e32 v90, v69
	v_mov_b32_e32 v91, v69
	v_pk_mul_f32 v[4:5], v[10:11], v[68:69]
	v_pk_mul_f32 v[2:3], v[2:3], v[68:69]
	v_mov_b32_e32 v10, v88
	v_mov_b32_e32 v11, v12
	v_pk_mul_f32 v[68:69], v[36:37], v[78:79]
	v_mov_b32_dpp v29, v44 row_shr:1 row_mask:0xf bank_mask:0xf
	v_mov_b32_dpp v28, v48 row_shr:1 row_mask:0xf bank_mask:0xf
	v_pk_fma_f32 v[68:69], v[10:11], v[34:35], v[68:69]
	v_pk_mul_f32 v[0:1], v[0:1], v[90:91]
	v_pk_fma_f32 v[28:29], v[32:33], v[28:29], v[68:69]
	v_mov_b32_e32 v68, v0
	v_mul_f32_e32 v0, 0xbfb8aa3b, v29
	v_pk_mul_f32 v[8:9], v[8:9], v[90:91]
	v_exp_f32_e32 v0, v0
	v_mov_b32_e32 v69, v8
	v_pk_mul_f32 v[90:91], v[68:69], v[34:35]
	v_pk_mul_f32 v[14:15], v[14:15], v[92:93]
	v_pk_fma_f32 v[90:91], v[10:11], v[36:37], v[90:91]
	v_add_f32_e32 v0, 1.0, v0
	v_pk_fma_f32 v[78:79], v[32:33], v[78:79], v[90:91]
	v_mov_b32_e32 v90, v48
	v_mov_b32_e32 v91, v44
	v_pk_mul_f32 v[6:7], v[6:7], v[92:93]
	v_pk_mul_f32 v[92:93], v[90:91], v[34:35]
	v_rcp_f32_e32 v0, v0
	v_mul_f32_e32 v8, 0xbfb8aa3b, v79
	v_pk_fma_f32 v[92:93], v[68:69], v[36:37], v[92:93]
	v_exp_f32_e32 v8, v8
	v_pk_fma_f32 v[10:11], v[10:11], v[32:33], v[92:93]
	v_mov_b32_e32 v92, v56
	v_mov_b32_e32 v93, v52
	v_pk_mul_f32 v[34:35], v[92:93], v[34:35]
	v_mul_f32_e32 v0, v29, v0
	v_pk_fma_f32 v[34:35], v[90:91], v[36:37], v[34:35]
	v_mov_b32_dpp v85, v53 row_shr:1 row_mask:0xf bank_mask:0xf
	v_pk_fma_f32 v[32:33], v[68:69], v[32:33], v[34:35]
	v_mul_f32_e32 v34, v28, v0
	v_add_f32_e32 v0, 1.0, v8
	v_mul_f32_e32 v8, 0xbfb8aa3b, v11
	v_exp_f32_e32 v8, v8
	v_mul_f32_e32 v12, 0xbfb8aa3b, v33
	v_exp_f32_e32 v12, v12
	v_rcp_f32_e32 v0, v0
	v_add_f32_e32 v8, 1.0, v8
	v_rcp_f32_e32 v8, v8
	v_add_f32_e32 v12, 1.0, v12
	v_rcp_f32_e32 v12, v12
	v_mul_f32_e32 v0, v79, v0
	v_mul_f32_e32 v35, v78, v0
	v_mul_f32_e32 v0, v11, v8
	v_mov_b32_dpp v84, v57 row_shr:1 row_mask:0xf bank_mask:0xf
	v_mul_f32_e32 v36, v10, v0
	v_mul_f32_e32 v0, v33, v12
	v_mov_b32_e32 v12, v89
	v_pk_mul_f32 v[10:11], v[106:107], v[84:85]
	v_mov_b32_e32 v44, v49
	v_mov_b32_dpp v87, v45 row_shr:1 row_mask:0xf bank_mask:0xf
	v_mov_b32_dpp v86, v49 row_shr:1 row_mask:0xf bank_mask:0xf
	v_pk_fma_f32 v[10:11], v[12:13], v[110:111], v[10:11]
	v_mov_b32_e32 v8, v1
	v_pk_mul_f32 v[28:29], v[44:45], v[110:111]
	v_mul_f32_e32 v32, v32, v0
	v_pk_fma_f32 v[10:11], v[74:75], v[86:87], v[10:11]
	v_pk_mul_f32 v[0:1], v[8:9], v[110:111]
	v_pk_fma_f32 v[28:29], v[8:9], v[106:107], v[28:29]
	v_pk_fma_f32 v[0:1], v[12:13], v[106:107], v[0:1]
	v_pk_fma_f32 v[12:13], v[12:13], v[74:75], v[28:29]
	v_mul_f32_e32 v28, 0xbfb8aa3b, v11
	v_exp_f32_e32 v33, v28
	v_pk_fma_f32 v[0:1], v[74:75], v[84:85], v[0:1]
	v_mov_b32_e32 v52, v57
	v_mul_f32_e32 v37, 0xbfb8aa3b, v1
	v_add_f32_e32 v33, 1.0, v33
	v_rcp_f32_e32 v33, v33
	v_exp_f32_e32 v37, v37
	v_pk_mul_f32 v[28:29], v[52:53], v[110:111]
	v_mov_b32_dpp v81, v54 row_shr:1 row_mask:0xf bank_mask:0xf
	v_pk_fma_f32 v[28:29], v[44:45], v[106:107], v[28:29]
	v_mul_f32_e32 v11, v11, v33
	v_pk_fma_f32 v[8:9], v[8:9], v[74:75], v[28:29]
	v_mul_f32_e32 v33, v10, v11
	v_add_f32_e32 v10, 1.0, v37
	v_mul_f32_e32 v11, 0xbfb8aa3b, v13
	v_rcp_f32_e32 v10, v10
	v_exp_f32_e32 v11, v11
	v_mul_f32_e32 v28, 0xbfb8aa3b, v9
	v_exp_f32_e32 v28, v28
	v_mul_f32_e32 v1, v1, v10
	v_add_f32_e32 v10, 1.0, v11
	v_rcp_f32_e32 v10, v10
	v_add_f32_e32 v11, 1.0, v28
	v_rcp_f32_e32 v11, v11
	v_mul_f32_e32 v37, v0, v1
	v_mul_f32_e32 v0, v13, v10
	v_mul_f32_e32 v44, v12, v0
	v_mul_f32_e32 v0, v9, v11
	v_mov_b32_dpp v80, v58 row_shr:1 row_mask:0xf bank_mask:0xf
	v_mul_f32_e32 v45, v8, v0
	v_mov_b32_e32 v0, v6
	v_mov_b32_e32 v1, v14
	v_pk_mul_f32 v[8:9], v[42:43], v[80:81]
	v_mov_b32_dpp v31, v46 row_shr:1 row_mask:0xf bank_mask:0xf
	v_mov_b32_dpp v30, v50 row_shr:1 row_mask:0xf bank_mask:0xf
	v_pk_fma_f32 v[8:9], v[0:1], v[40:41], v[8:9]
	v_mov_b32_e32 v10, v2
	v_pk_fma_f32 v[8:9], v[38:39], v[30:31], v[8:9]
	v_mov_b32_e32 v11, v4
	v_mul_f32_e32 v2, 0xbfb8aa3b, v9
	v_exp_f32_e32 v2, v2
	v_pk_mul_f32 v[12:13], v[10:11], v[40:41]
	v_mov_b32_e32 v28, v50
	v_pk_fma_f32 v[12:13], v[0:1], v[42:43], v[12:13]
	v_mov_b32_e32 v29, v46
	v_pk_fma_f32 v[12:13], v[38:39], v[80:81], v[12:13]
	v_add_f32_e32 v2, 1.0, v2
	v_pk_mul_f32 v[30:31], v[28:29], v[40:41]
	v_rcp_f32_e32 v2, v2
	v_mul_f32_e32 v4, 0xbfb8aa3b, v13
	v_pk_fma_f32 v[30:31], v[10:11], v[42:43], v[30:31]
	v_exp_f32_e32 v4, v4
	v_pk_fma_f32 v[0:1], v[0:1], v[38:39], v[30:31]
	v_mov_b32_e32 v30, v58
	v_mov_b32_e32 v31, v54
	v_pk_mul_f32 v[30:31], v[30:31], v[40:41]
	v_mul_f32_e32 v2, v9, v2
	v_pk_fma_f32 v[28:29], v[28:29], v[42:43], v[30:31]
	v_mov_b32_dpp v71, v55 row_shr:1 row_mask:0xf bank_mask:0xf
	v_pk_fma_f32 v[10:11], v[10:11], v[38:39], v[28:29]
	v_mul_f32_e32 v28, v8, v2
	v_add_f32_e32 v2, 1.0, v4
	v_mul_f32_e32 v4, 0xbfb8aa3b, v1
	v_exp_f32_e32 v4, v4
	v_mul_f32_e32 v6, 0xbfb8aa3b, v11
	v_exp_f32_e32 v6, v6
	v_rcp_f32_e32 v2, v2
	v_add_f32_e32 v4, 1.0, v4
	v_rcp_f32_e32 v4, v4
	v_add_f32_e32 v6, 1.0, v6
	v_rcp_f32_e32 v6, v6
	v_mul_f32_e32 v2, v13, v2
	v_mul_f32_e32 v1, v1, v4
	v_mul_f32_e32 v13, v0, v1
	v_mul_f32_e32 v0, v11, v6
	v_mov_b32_dpp v70, v59 row_shr:1 row_mask:0xf bank_mask:0xf
	v_mul_f32_e32 v10, v10, v0
	v_mov_b32_e32 v14, v7
	v_pk_mul_f32 v[0:1], v[108:109], v[70:71]
	v_mov_b32_dpp v73, v47 row_shr:1 row_mask:0xf bank_mask:0xf
	v_mov_b32_dpp v72, v51 row_shr:1 row_mask:0xf bank_mask:0xf
	v_pk_fma_f32 v[0:1], v[14:15], v[112:113], v[0:1]
	v_mov_b32_e32 v4, v3
	v_pk_fma_f32 v[0:1], v[76:77], v[72:73], v[0:1]
	v_mul_f32_e32 v12, v12, v2
	v_mul_f32_e32 v8, 0xbfb8aa3b, v1
	v_exp_f32_e32 v11, v8
	v_pk_mul_f32 v[2:3], v[4:5], v[112:113]
	v_mov_b32_e32 v46, v51
	v_pk_fma_f32 v[2:3], v[14:15], v[108:109], v[2:3]
	v_pk_mul_f32 v[6:7], v[46:47], v[112:113]
	v_pk_fma_f32 v[2:3], v[76:77], v[70:71], v[2:3]
	v_pk_fma_f32 v[6:7], v[4:5], v[108:109], v[6:7]
	v_add_f32_e32 v11, 1.0, v11
	v_pk_fma_f32 v[6:7], v[14:15], v[76:77], v[6:7]
	v_rcp_f32_e32 v11, v11
	v_mul_f32_e32 v14, 0xbfb8aa3b, v3
	v_exp_f32_e32 v14, v14
	v_mov_b32_e32 v54, v59
	v_pk_mul_f32 v[8:9], v[54:55], v[112:113]
	v_mul_f32_e32 v1, v1, v11
	v_pk_fma_f32 v[8:9], v[46:47], v[108:109], v[8:9]
	v_mul_f32_e32 v0, v0, v1
	v_pk_fma_f32 v[4:5], v[4:5], v[76:77], v[8:9]
	v_add_f32_e32 v1, 1.0, v14
	v_mul_f32_e32 v8, 0xbfb8aa3b, v7
	v_rcp_f32_e32 v1, v1
	v_exp_f32_e32 v8, v8
	v_mul_f32_e32 v9, 0xbfb8aa3b, v5
	v_exp_f32_e32 v9, v9
	v_mul_f32_e32 v1, v3, v1
	v_add_f32_e32 v3, 1.0, v8
	v_rcp_f32_e32 v3, v3
	v_add_f32_e32 v8, 1.0, v9
	v_rcp_f32_e32 v8, v8
	v_mul_f32_e32 v9, v2, v1
	v_mul_f32_e32 v1, v7, v3
	v_mul_f32_e32 v6, v6, v1
	v_mul_f32_e32 v1, v5, v8
	v_add_u32_e32 v94, 0x80, v146
	v_mul_f32_e32 v4, v4, v1
	v_cvt_pk_bf16_f32 v68, v34, v33
	v_cvt_pk_bf16_f32 v69, v28, v0
	v_mov_b64_e32 v[0:1], s[24:25]
	v_mad_i64_i32 v[2:3], s[30:31], v94, s58, v[0:1]
	v_lshl_add_u64 v[2:3], v[2:3], 0, v[82:83]
	global_store_dwordx4 v[2:3], v[66:69], off nt
	v_add_u32_e32 v2, 0x81, v146
	v_mad_i64_i32 v[2:3], s[30:31], v2, s58, v[0:1]
	v_lshl_add_u64 v[2:3], v[2:3], 0, v[82:83]
	v_cvt_pk_bf16_f32 v66, v35, v37
	v_cvt_pk_bf16_f32 v67, v12, v9
	global_store_dwordx4 v[2:3], v[64:67], off nt
	v_add_u32_e32 v2, 0x82, v146
	v_mad_i64_i32 v[2:3], s[30:31], v2, s58, v[0:1]
	v_lshl_add_u64 v[2:3], v[2:3], 0, v[82:83]
	v_cvt_pk_bf16_f32 v64, v36, v44
	v_cvt_pk_bf16_f32 v65, v13, v6
	global_store_dwordx4 v[2:3], v[62:65], off nt
	v_add_u32_e32 v2, 0x83, v146
	v_mad_i64_i32 v[0:1], s[30:31], v2, s58, v[0:1]
	v_lshl_add_u64 v[0:1], v[0:1], 0, v[82:83]
	v_cvt_pk_bf16_f32 v62, v32, v45
	v_cvt_pk_bf16_f32 v63, v10, v4
	global_store_dwordx4 v[0:1], v[60:63], off nt
	s_and_b64 vcc, exec, s[8:9]
	s_mov_b64 s[8:9], -1
	s_cbranch_vccnz .LBB0_450
	s_xor_b32 s8, s11, 0x1000
	s_add_i32 s11, s8, 0
	s_add_i32 s11, s11, 0x24010
	s_and_saveexec_b64 s[8:9], s[2:3]
	s_cbranch_execz .LBB0_472
	v_add3_u32 v0, s11, v215, v190
	s_waitcnt vmcnt(8)
	ds_write_b128 v0, v[16:19]
.LBB0_472:
	s_or_b64 exec, exec, s[8:9]
	s_waitcnt vmcnt(8)
	v_add_f32_e32 v0, v24, v25
	v_add_f32_e32 v1, v26, v27
	v_add_f32_e32 v0, v0, v1
	v_add_f32_e32 v1, v20, v21
	v_add_f32_e32 v2, v22, v23
	v_add_f32_e32 v1, v1, v2
	v_add_f32_e32 v0, v1, v0
	v_mov_b32_e32 v1, 0
	s_nop 1
	v_mov_b32_dpp v1, v0 quad_perm:[1,0,3,2] row_mask:0xf bank_mask:0xf
	s_and_saveexec_b64 s[8:9], s[4:5]
	s_xor_b64 s[8:9], exec, s[8:9]
	s_cbranch_execz .LBB0_449
	v_add_f32_e32 v0, v0, v1
	v_fmamk_f32 v0, v0, 0x3a800000, v216
	v_mul_f32_e32 v1, 0x4b800000, v0
	v_cmp_gt_f32_e32 vcc, s59, v0
	s_nop 1
	v_cndmask_b32_e32 v0, v0, v1, vcc
	v_rsq_f32_e32 v0, v0
	v_lshl_add_u32 v1, v211, 2, s11
	v_mul_f32_e32 v2, 0x45800000, v0
	v_cndmask_b32_e32 v0, v0, v2, vcc
	ds_write_b32 v1, v0 offset:3072
	s_branch .LBB0_449

.LBB0_790:
	s_cmpk_ge_u32 s14, 0xa00
	s_cbranch_scc1 .Lfa_kq_drain
	s_waitcnt vmcnt(16)
	s_branch .Lfa_kq_cont

.Lfa_kq_cont:
	v_add_f32_e32 v0, v28, v29
	v_add_f32_e32 v1, v30, v31
	v_add_f32_e32 v0, v0, v1
	v_add_f32_e32 v1, v24, v25
	v_add_f32_e32 v2, v26, v27
	v_add_f32_e32 v1, v1, v2
	v_add_f32_e32 v0, v1, v0
	ds_bpermute_b32 v1, v147, v0
	s_and_saveexec_b64 s[6:7], s[2:3]
	s_xor_b64 s[6:7], exec, s[6:7]
	s_cbranch_execz .LBB0_637
	s_waitcnt lgkmcnt(0)
	v_add_f32_e32 v0, v0, v1
	v_fmamk_f32 v0, v0, 0x3a800000, v181
	v_mul_f32_e32 v1, 0x4b800000, v0
	v_cmp_gt_f32_e32 vcc, s62, v0
	s_xor_b32 s8, s23, 0x1000
	s_nop 0
	v_cndmask_b32_e32 v0, v0, v1, vcc
	v_rsq_f32_e32 v0, v0
	s_nop 0
	v_mul_f32_e32 v1, 0x45800000, v0
	v_cndmask_b32_e32 v0, v0, v1, vcc
	v_add_u32_e32 v1, s8, v177
	ds_write_b32 v1, v0 offset:3072
	s_branch .LBB0_637

.LBB0_1656:
	v_mov_b32_e32 v88, v68
	v_mov_b32_e32 v89, v68
	v_mov_b32_e32 v92, v68
	v_mov_b32_e32 v93, v68
	v_pk_mul_f32 v[12:13], v[12:13], v[88:89]
	v_pk_mul_f32 v[88:89], v[4:5], v[88:89]
	v_mov_b32_e32 v68, v69
	v_mov_b32_dpp v79, v52 row_shr:1 row_mask:0xf bank_mask:0xf
	v_mov_b32_dpp v78, v56 row_shr:1 row_mask:0xf bank_mask:0xf
	v_mov_b32_e32 v90, v69
	v_mov_b32_e32 v91, v69
	v_pk_mul_f32 v[4:5], v[10:11], v[68:69]
	v_pk_mul_f32 v[2:3], v[2:3], v[68:69]
	v_mov_b32_e32 v10, v88
	v_mov_b32_e32 v11, v12
	v_pk_mul_f32 v[68:69], v[36:37], v[78:79]
	v_mov_b32_dpp v29, v44 row_shr:1 row_mask:0xf bank_mask:0xf
	v_mov_b32_dpp v28, v48 row_shr:1 row_mask:0xf bank_mask:0xf
	v_pk_fma_f32 v[68:69], v[10:11], v[34:35], v[68:69]
	v_pk_mul_f32 v[0:1], v[0:1], v[90:91]
	v_pk_fma_f32 v[28:29], v[32:33], v[28:29], v[68:69]
	v_mov_b32_e32 v68, v0
	v_mul_f32_e32 v0, 0xbfb8aa3b, v29
	v_pk_mul_f32 v[8:9], v[8:9], v[90:91]
	v_exp_f32_e32 v0, v0
	v_mov_b32_e32 v69, v8
	v_pk_mul_f32 v[90:91], v[68:69], v[34:35]
	v_pk_mul_f32 v[14:15], v[14:15], v[92:93]
	v_pk_fma_f32 v[90:91], v[10:11], v[36:37], v[90:91]
	v_add_f32_e32 v0, 1.0, v0
	v_pk_fma_f32 v[78:79], v[32:33], v[78:79], v[90:91]
	v_mov_b32_e32 v90, v48
	v_mov_b32_e32 v91, v44
	v_pk_mul_f32 v[6:7], v[6:7], v[92:93]
	v_pk_mul_f32 v[92:93], v[90:91], v[34:35]
	v_rcp_f32_e32 v0, v0
	v_mul_f32_e32 v8, 0xbfb8aa3b, v79
	v_pk_fma_f32 v[92:93], v[68:69], v[36:37], v[92:93]
	v_exp_f32_e32 v8, v8
	v_pk_fma_f32 v[10:11], v[10:11], v[32:33], v[92:93]
	v_mov_b32_e32 v92, v56
	v_mov_b32_e32 v93, v52
	v_pk_mul_f32 v[34:35], v[92:93], v[34:35]
	v_mul_f32_e32 v0, v29, v0
	v_pk_fma_f32 v[34:35], v[90:91], v[36:37], v[34:35]
	v_mov_b32_dpp v85, v53 row_shr:1 row_mask:0xf bank_mask:0xf
	v_pk_fma_f32 v[32:33], v[68:69], v[32:33], v[34:35]
	v_mul_f32_e32 v34, v28, v0
	v_add_f32_e32 v0, 1.0, v8
	v_mul_f32_e32 v8, 0xbfb8aa3b, v11
	v_exp_f32_e32 v8, v8
	v_mul_f32_e32 v12, 0xbfb8aa3b, v33
	v_exp_f32_e32 v12, v12
	v_rcp_f32_e32 v0, v0
	v_add_f32_e32 v8, 1.0, v8
	v_rcp_f32_e32 v8, v8
	v_add_f32_e32 v12, 1.0, v12
	v_rcp_f32_e32 v12, v12
	v_mul_f32_e32 v0, v79, v0
	v_mul_f32_e32 v35, v78, v0
	v_mul_f32_e32 v0, v11, v8
	v_mov_b32_dpp v84, v57 row_shr:1 row_mask:0xf bank_mask:0xf
	v_mul_f32_e32 v36, v10, v0
	v_mul_f32_e32 v0, v33, v12
	v_mov_b32_e32 v12, v89
	v_pk_mul_f32 v[10:11], v[106:107], v[84:85]
	v_mov_b32_e32 v44, v49
	v_mov_b32_dpp v87, v45 row_shr:1 row_mask:0xf bank_mask:0xf
	v_mov_b32_dpp v86, v49 row_shr:1 row_mask:0xf bank_mask:0xf
	v_pk_fma_f32 v[10:11], v[12:13], v[110:111], v[10:11]
	v_mov_b32_e32 v8, v1
	v_pk_mul_f32 v[28:29], v[44:45], v[110:111]
	v_mul_f32_e32 v32, v32, v0
	v_pk_fma_f32 v[10:11], v[74:75], v[86:87], v[10:11]
	v_pk_mul_f32 v[0:1], v[8:9], v[110:111]
	v_pk_fma_f32 v[28:29], v[8:9], v[106:107], v[28:29]
	v_pk_fma_f32 v[0:1], v[12:13], v[106:107], v[0:1]
	v_pk_fma_f32 v[12:13], v[12:13], v[74:75], v[28:29]
	v_mul_f32_e32 v28, 0xbfb8aa3b, v11
	v_exp_f32_e32 v33, v28
	v_pk_fma_f32 v[0:1], v[74:75], v[84:85], v[0:1]
	v_mov_b32_e32 v52, v57
	v_mul_f32_e32 v37, 0xbfb8aa3b, v1
	v_add_f32_e32 v33, 1.0, v33
	v_rcp_f32_e32 v33, v33
	v_exp_f32_e32 v37, v37
	v_pk_mul_f32 v[28:29], v[52:53], v[110:111]
	v_mov_b32_dpp v81, v54 row_shr:1 row_mask:0xf bank_mask:0xf
	v_pk_fma_f32 v[28:29], v[44:45], v[106:107], v[28:29]
	v_mul_f32_e32 v11, v11, v33
	v_pk_fma_f32 v[8:9], v[8:9], v[74:75], v[28:29]
	v_mul_f32_e32 v33, v10, v11
	v_add_f32_e32 v10, 1.0, v37
	v_mul_f32_e32 v11, 0xbfb8aa3b, v13
	v_rcp_f32_e32 v10, v10
	v_exp_f32_e32 v11, v11
	v_mul_f32_e32 v28, 0xbfb8aa3b, v9
	v_exp_f32_e32 v28, v28
	v_mul_f32_e32 v1, v1, v10
	v_add_f32_e32 v10, 1.0, v11
	v_rcp_f32_e32 v10, v10
	v_add_f32_e32 v11, 1.0, v28
	v_rcp_f32_e32 v11, v11
	v_mul_f32_e32 v37, v0, v1
	v_mul_f32_e32 v0, v13, v10
	v_mul_f32_e32 v44, v12, v0
	v_mul_f32_e32 v0, v9, v11
	v_mov_b32_dpp v80, v58 row_shr:1 row_mask:0xf bank_mask:0xf
	v_mul_f32_e32 v45, v8, v0
	v_mov_b32_e32 v0, v6
	v_mov_b32_e32 v1, v14
	v_pk_mul_f32 v[8:9], v[42:43], v[80:81]
	v_mov_b32_dpp v31, v46 row_shr:1 row_mask:0xf bank_mask:0xf
	v_mov_b32_dpp v30, v50 row_shr:1 row_mask:0xf bank_mask:0xf
	v_pk_fma_f32 v[8:9], v[0:1], v[40:41], v[8:9]
	v_mov_b32_e32 v10, v2
	v_pk_fma_f32 v[8:9], v[38:39], v[30:31], v[8:9]
	v_mov_b32_e32 v11, v4
	v_mul_f32_e32 v2, 0xbfb8aa3b, v9
	v_exp_f32_e32 v2, v2
	v_pk_mul_f32 v[12:13], v[10:11], v[40:41]
	v_mov_b32_e32 v28, v50
	v_pk_fma_f32 v[12:13], v[0:1], v[42:43], v[12:13]
	v_mov_b32_e32 v29, v46
	v_pk_fma_f32 v[12:13], v[38:39], v[80:81], v[12:13]
	v_add_f32_e32 v2, 1.0, v2
	v_pk_mul_f32 v[30:31], v[28:29], v[40:41]
	v_rcp_f32_e32 v2, v2
	v_mul_f32_e32 v4, 0xbfb8aa3b, v13
	v_pk_fma_f32 v[30:31], v[10:11], v[42:43], v[30:31]
	v_exp_f32_e32 v4, v4
	v_pk_fma_f32 v[0:1], v[0:1], v[38:39], v[30:31]
	v_mov_b32_e32 v30, v58
	v_mov_b32_e32 v31, v54
	v_pk_mul_f32 v[30:31], v[30:31], v[40:41]
	v_mul_f32_e32 v2, v9, v2
	v_pk_fma_f32 v[28:29], v[28:29], v[42:43], v[30:31]
	v_mov_b32_dpp v71, v55 row_shr:1 row_mask:0xf bank_mask:0xf
	v_pk_fma_f32 v[10:11], v[10:11], v[38:39], v[28:29]
	v_mul_f32_e32 v28, v8, v2
	v_add_f32_e32 v2, 1.0, v4
	v_mul_f32_e32 v4, 0xbfb8aa3b, v1
	v_exp_f32_e32 v4, v4
	v_mul_f32_e32 v6, 0xbfb8aa3b, v11
	v_exp_f32_e32 v6, v6
	v_rcp_f32_e32 v2, v2
	v_add_f32_e32 v4, 1.0, v4
	v_rcp_f32_e32 v4, v4
	v_add_f32_e32 v6, 1.0, v6
	v_rcp_f32_e32 v6, v6
	v_mul_f32_e32 v2, v13, v2
	v_mul_f32_e32 v1, v1, v4
	v_mul_f32_e32 v13, v0, v1
	v_mul_f32_e32 v0, v11, v6
	v_mov_b32_dpp v70, v59 row_shr:1 row_mask:0xf bank_mask:0xf
	v_mul_f32_e32 v10, v10, v0
	v_mov_b32_e32 v14, v7
	v_pk_mul_f32 v[0:1], v[108:109], v[70:71]
	v_mov_b32_dpp v73, v47 row_shr:1 row_mask:0xf bank_mask:0xf
	v_mov_b32_dpp v72, v51 row_shr:1 row_mask:0xf bank_mask:0xf
	v_pk_fma_f32 v[0:1], v[14:15], v[112:113], v[0:1]
	v_mov_b32_e32 v4, v3
	v_pk_fma_f32 v[0:1], v[76:77], v[72:73], v[0:1]
	v_mul_f32_e32 v12, v12, v2
	v_mul_f32_e32 v8, 0xbfb8aa3b, v1
	v_exp_f32_e32 v11, v8
	v_pk_mul_f32 v[2:3], v[4:5], v[112:113]
	v_mov_b32_e32 v46, v51
	v_pk_fma_f32 v[2:3], v[14:15], v[108:109], v[2:3]
	v_pk_mul_f32 v[6:7], v[46:47], v[112:113]
	v_pk_fma_f32 v[2:3], v[76:77], v[70:71], v[2:3]
	v_pk_fma_f32 v[6:7], v[4:5], v[108:109], v[6:7]
	v_add_f32_e32 v11, 1.0, v11
	v_pk_fma_f32 v[6:7], v[14:15], v[76:77], v[6:7]
	v_rcp_f32_e32 v11, v11
	v_mul_f32_e32 v14, 0xbfb8aa3b, v3
	v_exp_f32_e32 v14, v14
	v_mov_b32_e32 v54, v59
	v_pk_mul_f32 v[8:9], v[54:55], v[112:113]
	v_mul_f32_e32 v1, v1, v11
	v_pk_fma_f32 v[8:9], v[46:47], v[108:109], v[8:9]
	v_mul_f32_e32 v0, v0, v1
	v_pk_fma_f32 v[4:5], v[4:5], v[76:77], v[8:9]
	v_add_f32_e32 v1, 1.0, v14
	v_mul_f32_e32 v8, 0xbfb8aa3b, v7
	v_rcp_f32_e32 v1, v1
	v_exp_f32_e32 v8, v8
	v_mul_f32_e32 v9, 0xbfb8aa3b, v5
	v_exp_f32_e32 v9, v9
	v_mul_f32_e32 v1, v3, v1
	v_add_f32_e32 v3, 1.0, v8
	v_rcp_f32_e32 v3, v3
	v_add_f32_e32 v8, 1.0, v9
	v_rcp_f32_e32 v8, v8
	v_mul_f32_e32 v9, v2, v1
	v_mul_f32_e32 v1, v7, v3
	v_mul_f32_e32 v6, v6, v1
	v_mul_f32_e32 v1, v5, v8
	v_add_u32_e32 v94, 0x80, v146
	v_mul_f32_e32 v4, v4, v1
	v_cvt_pk_bf16_f32 v68, v34, v33
	v_cvt_pk_bf16_f32 v69, v28, v0
	v_mov_b64_e32 v[0:1], s[24:25]
	v_mad_i64_i32 v[2:3], s[26:27], v94, s54, v[0:1]
	v_lshl_add_u64 v[2:3], v[2:3], 0, v[82:83]
	global_store_dwordx4 v[2:3], v[66:69], off nt
	v_add_u32_e32 v2, 0x81, v146
	v_mad_i64_i32 v[2:3], s[26:27], v2, s54, v[0:1]
	v_lshl_add_u64 v[2:3], v[2:3], 0, v[82:83]
	v_cvt_pk_bf16_f32 v66, v35, v37
	v_cvt_pk_bf16_f32 v67, v12, v9
	global_store_dwordx4 v[2:3], v[64:67], off nt
	v_add_u32_e32 v2, 0x82, v146
	v_mad_i64_i32 v[2:3], s[26:27], v2, s54, v[0:1]
	v_lshl_add_u64 v[2:3], v[2:3], 0, v[82:83]
	v_cvt_pk_bf16_f32 v64, v36, v44
	v_cvt_pk_bf16_f32 v65, v13, v6
	global_store_dwordx4 v[2:3], v[62:65], off nt
	v_add_u32_e32 v2, 0x83, v146
	v_mad_i64_i32 v[0:1], s[26:27], v2, s54, v[0:1]
	v_lshl_add_u64 v[0:1], v[0:1], 0, v[82:83]
	v_cvt_pk_bf16_f32 v62, v32, v45
	v_cvt_pk_bf16_f32 v63, v10, v4
	global_store_dwordx4 v[0:1], v[60:63], off nt
	s_and_b64 vcc, exec, s[8:9]
	s_mov_b64 s[8:9], -1
	s_cbranch_vccnz .LBB0_1637
	s_xor_b32 s8, s11, 0x1000
	s_add_i32 s11, s8, 0
	s_add_i32 s11, s11, 0x24010
	s_and_saveexec_b64 s[8:9], s[2:3]
	s_cbranch_execz .LBB0_1659
	v_add3_u32 v0, s11, v215, v190
	s_waitcnt vmcnt(8)
	ds_write_b128 v0, v[16:19]
.LBB0_1659:
	s_or_b64 exec, exec, s[8:9]
	s_waitcnt vmcnt(8)
	v_add_f32_e32 v0, v24, v25
	v_add_f32_e32 v1, v26, v27
	v_add_f32_e32 v0, v0, v1
	v_add_f32_e32 v1, v20, v21
	v_add_f32_e32 v2, v22, v23
	v_add_f32_e32 v1, v1, v2
	v_add_f32_e32 v0, v1, v0
	v_mov_b32_e32 v1, 0
	s_nop 1
	v_mov_b32_dpp v1, v0 quad_perm:[1,0,3,2] row_mask:0xf bank_mask:0xf
	s_and_saveexec_b64 s[8:9], s[4:5]
	s_xor_b64 s[8:9], exec, s[8:9]
	s_cbranch_execz .LBB0_1636
	v_add_f32_e32 v0, v0, v1
	v_fmamk_f32 v0, v0, 0x3a800000, v216
	v_mul_f32_e32 v1, 0x4b800000, v0
	v_cmp_gt_f32_e32 vcc, s55, v0
	s_nop 1
	v_cndmask_b32_e32 v0, v0, v1, vcc
	v_rsq_f32_e32 v0, v0
	v_lshl_add_u32 v1, v211, 2, s11
	v_mul_f32_e32 v2, 0x45800000, v0
	v_cndmask_b32_e32 v0, v0, v2, vcc
	ds_write_b32 v1, v0 offset:3072
	s_branch .LBB0_1636
